# MX loop: exact per-wave-class vmcnt waits (waves 0-3 no longer wait on just-issued K/Q loads); plus v003 edits
# speedup vs baseline: 1.0104x; 1.0104x over previous
; #define MX_LOADK(ch) do { const int r0_ = lrowb + (ch) * 64; const char* kr_ = (const char*)(kb + (size_t)r0_ * qpitch); \
;             _Pragma("unroll") for (int i = 0; i < 4; ++i) pk[i] = *(const u32x4*)(kr_ + i * qstep16 + voq); \
;             if (tid < 256) pv = *(const u32x4*)((const char*)(vb + (size_t)r0_ * NPC) + vov); } while (0)
; DI void phase_mixer(const Params& p, int seg, LAS unsigned char* lds, int G, int bid) {
;     ...
;             MX_STAGEK(1.0f);
;             if (ch + 1 < NCH) MX_LOADK(ch + 1);
.LBB0_602:
	s_and_b64 vcc, exec, s[42:43]
	s_cbranch_vccnz .Lmx_wa1
	s_waitcnt vmcnt(7)
	ds_write_b128 v229, v[36:39] offset:33792
	s_waitcnt vmcnt(6)
	ds_write_b128 v230, v[32:35] offset:33792
	s_waitcnt vmcnt(5)
	ds_write_b128 v231, v[44:47] offset:33792
	s_waitcnt vmcnt(4)
	ds_write_b128 v232, v[40:43] offset:33792
	s_branch .Lmx_wa2
.Lmx_wa1:
	s_waitcnt vmcnt(10)
	ds_write_b128 v229, v[36:39] offset:33792
	s_waitcnt vmcnt(9)
	ds_write_b128 v230, v[32:35] offset:33792
	s_waitcnt vmcnt(8)
	ds_write_b128 v231, v[44:47] offset:33792
	s_waitcnt vmcnt(7)
	ds_write_b128 v232, v[40:43] offset:33792
	s_waitcnt vmcnt(6)
.Lmx_wa2:
	s_and_saveexec_b64 vcc, s[42:43]
	v_add_u32_e32 v0, v218, v220
	ds_write_b128 v0, v[4:7]
	s_or_b64 exec, exec, vcc
	v_lshl_add_u64 v[2:3], s[92:93], 0, v[192:193]
	v_lshl_add_u64 v[32:33], s[92:93], 0, v[198:199]
	global_load_dwordx4 v[36:39], v[2:3], off
	s_nop 0
	global_load_dwordx4 v[32:35], v[32:33], off
	v_lshl_add_u64 v[2:3], s[92:93], 0, v[194:195]
	v_lshl_add_u64 v[40:41], s[92:93], 0, v[196:197]
	global_load_dwordx4 v[44:47], v[2:3], off
	s_nop 0
	global_load_dwordx4 v[40:43], v[40:41], off
	s_and_saveexec_b64 vcc, s[42:43]
	s_cbranch_execz .LBB0_606
	v_lshl_add_u64 v[2:3], s[92:93], 0, v[182:183]
	global_load_dwordx4 v[4:7], v[2:3], off

; DI void phase_mixer(const Params& p, int seg, LAS unsigned char* lds, int G, int bid) {
;     ...
;             {
;                 s16x4 t0[4], t1r[4], tv[12];
;                 int lnB = lane;
;                 const int j16 = lnB & 15, h4 = lnB >> 4;
;                 const unsigned addr0 = ldsb + L_KI + (8 * h4 + (j16 >> 2)) * QP + (2 * wave) * 32 + 8 * (lnB & 3);
;                 const unsigned addrv = ldsb + L_VI + (8 * h4 + (j16 >> 2)) * VP2 + 8 * (lnB & 3);
;                 asm volatile("ds_read_b64_tr_b16 %0, %8\n\tds_read_b64_tr_b16 %1, %8 offset:2112\n\tds_read_b64_tr_b16 %2, %8 offset:16896\n\tds_read_b64_tr_b16 %3, %8 offset:19008\n\t"
;                              "ds_read_b64_tr_b16 %4, %8 offset:32\n\tds_read_b64_tr_b16 %5, %8 offset:2144\n\tds_read_b64_tr_b16 %6, %8 offset:16928\n\tds_read_b64_tr_b16 %7, %8 offset:19040\n\ts_waitcnt lgkmcnt(0)"
;                              : "=&v"(t0[0]), "=&v"(t0[1]), "=&v"(t0[2]), "=&v"(t0[3]), "=&v"(t1r[0]), "=&v"(t1r[1]), "=&v"(t1r[2]), "=&v"(t1r[3]) : "v"(addr0) : "memory");
;                 asm volatile("ds_read_b64_tr_b16 %0, %12\n\tds_read_b64_tr_b16 %1, %12 offset:448\n\tds_read_b64_tr_b16 %2, %12 offset:3584\n\tds_read_b64_tr_b16 %3, %12 offset:4032\n\t"
;                              "ds_read_b64_tr_b16 %4, %12 offset:32\n\tds_read_b64_tr_b16 %5, %12 offset:480\n\tds_read_b64_tr_b16 %6, %12 offset:3616\n\tds_read_b64_tr_b16 %7, %12 offset:4064\n\t"
;                              "ds_read_b64_tr_b16 %8, %12 offset:64\n\tds_read_b64_tr_b16 %9, %12 offset:512\n\tds_read_b64_tr_b16 %10, %12 offset:3648\n\tds_read_b64_tr_b16 %11, %12 offset:4096\n\ts_waitcnt lgkmcnt(0)"
;                              : "=&v"(tv[0]), "=&v"(tv[1]), "=&v"(tv[2]), "=&v"(tv[3]), "=&v"(tv[4]), "=&v"(tv[5]), "=&v"(tv[6]), "=&v"(tv[7]), "=&v"(tv[8]), "=&v"(tv[9]), "=&v"(tv[10]), "=&v"(tv[11]) : "v"(addrv) : "memory");
;                 __builtin_amdgcn_sched_barrier(0);
; #pragma unroll
;                 for (int v = 0; v < 3; ++v) if (v < nvt) {
;                     const bf16x8 vb0 = __builtin_shufflevector(tv[4 * v], tv[4 * v + 1], 0, 1, 2, 3, 4, 5, 6, 7);
;                     C[0][v] = __builtin_amdgcn_mfma_f32_16x16x32_bf16(__builtin_shufflevector(t0[0], t0[1], 0, 1, 2, 3, 4, 5, 6, 7), vb0, C[0][v], 0, 0, 0);
.LBB0_610:
	ds_read_b64_tr_b16 v[76:77], v221
	ds_read_b64_tr_b16 v[78:79], v221 offset:2112
	ds_read_b64_tr_b16 v[68:69], v221 offset:16896
	ds_read_b64_tr_b16 v[70:71], v221 offset:19008
	ds_read_b64_tr_b16 v[72:73], v221 offset:32
	ds_read_b64_tr_b16 v[74:75], v221 offset:2144
	ds_read_b64_tr_b16 v[64:65], v221 offset:16928
	ds_read_b64_tr_b16 v[66:67], v221 offset:19040
	s_waitcnt lgkmcnt(0)
	ds_read_b64_tr_b16 v[100:101], v222
	ds_read_b64_tr_b16 v[102:103], v222 offset:448
	ds_read_b64_tr_b16 v[88:89], v222 offset:3584
	ds_read_b64_tr_b16 v[90:91], v222 offset:4032
	ds_read_b64_tr_b16 v[96:97], v222 offset:32
	ds_read_b64_tr_b16 v[98:99], v222 offset:480
	ds_read_b64_tr_b16 v[84:85], v222 offset:3616
	ds_read_b64_tr_b16 v[86:87], v222 offset:4064
	ds_read_b64_tr_b16 v[92:93], v222 offset:64
	ds_read_b64_tr_b16 v[94:95], v222 offset:512
	ds_read_b64_tr_b16 v[80:81], v222 offset:3648
	ds_read_b64_tr_b16 v[82:83], v222 offset:4096
	s_waitcnt lgkmcnt(0)
	s_nop 0
	v_mfma_f32_16x16x32_bf16 v[12:15], v[76:79], v[100:103], v[12:15]
	s_and_b64 vcc, exec, s[42:43]
	s_cbranch_vccnz .Lmx_wm1
	s_waitcnt vmcnt(6)
	s_branch .Lmx_wm2
.Lmx_wm1:
	s_waitcnt vmcnt(8)
.Lmx_wm2:
	v_max_f32_e32 v0, v234, v234
	s_add_u32 s35, s35, 64
	s_addc_u32 s22, s22, 0
	v_mfma_f32_16x16x32_bf16 v[8:11], v[76:79], v[96:99], v[8:11]
	s_add_i32 s23, s23, -1
	s_mov_b64 s[18:19], 0x1000
	v_lshl_add_u64 v[172:173], v[172:173], 0, s[54:55]
	v_mfma_f32_16x16x32_bf16 v[16:19], v[76:79], v[92:95], v[16:19]
	v_lshl_add_u64 v[174:175], v[174:175], 0, s[56:57]
	v_lshl_add_u64 v[176:177], v[176:177], 0, s[18:19]
	v_lshl_add_u64 v[178:179], v[178:179], 0, s[54:55]
	v_mfma_f32_16x16x32_bf16 v[20:23], v[72:75], v[100:103], v[20:23]
	v_lshl_add_u64 v[182:183], v[182:183], 0, s[56:57]
	v_lshl_add_u64 v[180:181], v[180:181], 0, s[56:57]
	v_lshl_add_u64 v[184:185], v[184:185], 0, s[26:27]
	v_mfma_f32_16x16x32_bf16 v[28:31], v[72:75], v[96:99], v[28:31]
	v_lshl_add_u64 v[186:187], v[186:187], 0, s[26:27]
	v_lshl_add_u64 v[188:189], v[188:189], 0, s[26:27]
	v_lshl_add_u64 v[190:191], v[190:191], 0, s[26:27]
	v_mfma_f32_16x16x32_bf16 v[12:15], v[68:71], v[88:91], v[12:15]
	v_lshl_add_u64 v[192:193], v[192:193], 0, s[26:27]
	v_lshl_add_u64 v[194:195], v[194:195], 0, s[26:27]
	v_lshl_add_u64 v[196:197], v[196:197], 0, s[26:27]
	v_mfma_f32_16x16x32_bf16 v[24:27], v[72:75], v[92:95], v[24:27]
	s_cmp_eq_u32 s23, 0
	s_nop 2
	v_pk_mul_f32 v[14:15], v[158:159], v[14:15] op_sel_hi:[0,1]
	v_pk_mul_f32 v[12:13], v[158:159], v[12:13] op_sel_hi:[0,1]
	v_mfma_f32_16x16x32_bf16 v[8:11], v[68:71], v[84:87], v[8:11]
	v_cvt_pk_bf16_f32 v2, v12, v13
	v_cvt_pk_bf16_f32 v3, v14, v15
	ds_write_b64 v228, v[2:3]
	v_mfma_f32_16x16x32_bf16 v[16:19], v[68:71], v[80:83], v[16:19]
	v_lshl_add_u64 v[198:199], v[198:199], 0, s[26:27]
	s_nop 2
	v_pk_mul_f32 v[10:11], v[158:159], v[10:11] op_sel_hi:[0,1]
	v_pk_mul_f32 v[8:9], v[158:159], v[8:9] op_sel_hi:[0,1]
	v_mfma_f32_16x16x32_bf16 v[20:23], v[64:67], v[88:91], v[20:23]
	v_cvt_pk_bf16_f32 v2, v8, v9
	v_pk_mul_f32 v[18:19], v[158:159], v[18:19] op_sel_hi:[0,1]
	v_pk_mul_f32 v[16:17], v[158:159], v[16:17] op_sel_hi:[0,1]
	v_mfma_f32_16x16x32_bf16 v[28:31], v[64:67], v[84:87], v[28:31]
	v_cvt_pk_bf16_f32 v3, v10, v11
	s_nop 2
	v_pk_mul_f32 v[22:23], v[158:159], v[22:23] op_sel_hi:[0,1]
	v_pk_mul_f32 v[20:21], v[158:159], v[20:21] op_sel_hi:[0,1]
	v_mfma_f32_16x16x32_bf16 v[24:27], v[64:67], v[80:83], v[24:27]
	ds_write_b64 v228, v[2:3] offset:8448
	v_cvt_pk_bf16_f32 v2, v16, v17
	v_cvt_pk_bf16_f32 v3, v18, v19
	v_pk_mul_f32 v[30:31], v[158:159], v[30:31] op_sel_hi:[0,1]
	v_pk_mul_f32 v[28:29], v[158:159], v[28:29] op_sel_hi:[0,1]
	ds_write_b64 v228, v[2:3] offset:16896
	v_cvt_pk_bf16_f32 v2, v20, v21
	v_cvt_pk_bf16_f32 v3, v22, v23
	v_pk_mul_f32 v[26:27], v[158:159], v[26:27] op_sel_hi:[0,1]
	v_pk_mul_f32 v[24:25], v[158:159], v[24:25] op_sel_hi:[0,1]
	ds_write_b64 v233, v[2:3]
	v_cvt_pk_bf16_f32 v2, v28, v29
	v_cvt_pk_bf16_f32 v3, v30, v31
	ds_write_b64 v233, v[2:3] offset:8448
	v_cvt_pk_bf16_f32 v2, v24, v25
	v_cvt_pk_bf16_f32 v3, v26, v27
	ds_write_b64 v233, v[2:3] offset:16896
	s_cbranch_vccnz .Lmx_wq1
	ds_write_b128 v229, v[48:51]
	ds_write_b128 v230, v[52:55]
	s_waitcnt vmcnt(5)
	ds_write_b128 v231, v[56:59]
	s_waitcnt vmcnt(4)
	ds_write_b128 v232, v[60:63]
	s_branch .Lmx_wq2
.Lmx_wq1:
	s_waitcnt vmcnt(12)
	ds_write_b128 v229, v[48:51]
	s_waitcnt vmcnt(11)
	ds_write_b128 v230, v[52:55]
	s_waitcnt vmcnt(10)
	ds_write_b128 v231, v[56:59]
	s_waitcnt vmcnt(9)
	ds_write_b128 v232, v[60:63]
	s_waitcnt vmcnt(7)
.Lmx_wq2:
	v_max_f32_e32 v2, v235, v235
	v_max_f32_e32 v0, v2, v0
	v_add_f32_e32 v0, v236, v0
	v_mul_f32_e32 v0, 0xbfb8aa3b, v0
	v_exp_f32_e32 v237, v0
	s_waitcnt lgkmcnt(0)
	s_barrier
	s_cbranch_scc1 .LBB0_612
	v_mov_b32_e32 v158, v160
	v_mov_b64_e32 v[2:3], v[156:157]
	v_mov_b64_e32 v[200:201], v[154:155]
	v_mov_b32_e32 v239, v238
	s_andn2_b64 vcc, exec, s[78:79]
	v_mov_b32_e32 v160, v153
	s_cbranch_vccz .LBB0_593
	s_branch .LBB0_594
